# v7 with the attention-prologue vmcnt(0) drains replaced by same-size s_nop (byte layout of v7 preserved)
# speedup vs baseline: 1.0003x; 1.0003x over previous
; #define FA_WAIT_NI() do { if constexpr (NI == 5) asm volatile("s_waitcnt vmcnt(5)" ::: "memory"); else asm volatile("s_waitcnt vmcnt(4)" ::: "memory"); } while (0)
; template <int DQK, bool HAS_LSE>
; __device__ __forceinline__ void unit(LAS unsigned char* lds, const Desc& d) {
;     ...
;     f32x16 o[4];
; #pragma unroll
;     for (int db = 0; db < 4; ++db)
; #pragma unroll
;         for (int i = 0; i < 16; ++i) o[db][i] = 0.f;
;     float m = NEG, l = 0.f;
;     int kso[KINST], vso[2]; bool kpe_[KINST];
; #pragma unroll
;     for (int i = 0; i < KINST; ++i) { const int q = 64 * (KINST * w + i) + lane, row = q / KCH, pos = q % KCH;
;         const int c = (DQK == 192) ? ((pos & ~7) | ((pos & 7) ^ ((row >> 1) & 7))) : (pos ^ (row & 15));
;         kpe_[i] = (DQK == 192) && (c >= 16);
;         kso[i] = kpe_[i] ? row * (int)d.kps + 8 * (c - 16) : row * (int)d.ks + 8 * c; }
; #pragma unroll
;     for (int i = 0; i < 2; ++i) { const int q = 64 * (2 * w + i) + lane, sub = q >> 5, wi = q & 31, key = 8 * (sub >> 2) + (wi >> 2), ch = (sub & 3) * 4 + (wi & 3);
;         vso[i] = key * (int)d.vs + 8 * ch; }
;     ...
;     int koff[NKO];
; #pragma unroll
;     for (int j = 0; j < NKO; ++j) koff[j] = (DQK == 192) ? (r * KROW + 16 * ((2 * j + hi) ^ ((r >> 1) & 7))) : (r * KROW + 16 * ((2 * j + hi) ^ (r & 15)));
;     const int vfo = LDS_V + (4 * hi + ((lane & 15) >> 2)) * 64 + ((lane >> 4) & 1) * 32 + (lane & 3) * 8;
;     ...
;     constexpr int NI = KINST + 2;
;     ...
;     FA_DMA(d.t_lo, 0, 0);
;     if (d.t_lo + 1 < d.t_hi) { FA_DMA(d.t_lo + 1, 1, 1); FA_WAIT_NI(); } else { asm volatile("s_waitcnt vmcnt(0)" ::: "memory"); }
;     __builtin_amdgcn_s_barrier();
;     int slot = 0;
; #pragma unroll 1
;     for (int t = d.t_lo; t < d.t_hi; ++t) {
; __global__ void __launch_bounds__(NWAVES * 64, 2) mega_fwd(Args args) {
;     ...
;                             dsc.slope2 = __builtin_amdgcn_exp2f(-(float)(g * DH + h + 1) * (1.0f / 3.0f)) * (float)dil * LOG2E;
.LBB0_513:
	s_cmp_ge_u32 s58, s59
	s_mov_b32 s64, 0
	s_barrier
	s_cbranch_scc1 .LBB0_529
	s_lshl_b32 s4, s6, 3
	s_or_b32 s4, s47, s4
	s_add_i32 s4, s4, 1
	v_cvt_f32_i32_e32 v8, s4
	s_lshl_b32 s4, 1, s21
	v_cvt_f32_u32_e32 v9, s4
	v_and_b32_e32 v10, 15, v5
	v_mul_f32_e32 v8, 0xbeaaaaab, v8
	v_exp_f32_e32 v8, v8
	s_add_i32 s22, s56, s22
	v_lshlrev_b32_e32 v174, 2, v6
	v_bitop3_b32 v11, v6, v5, 15 bitop3:0x78
	v_mul_f32_e32 v8, v8, v9
	v_bitop3_b32 v9, v6, v10, 2 bitop3:0x36
	v_lshlrev_b32_e32 v167, 4, v9
	v_bitop3_b32 v9, v6, v10, 4 bitop3:0x36
	v_lshlrev_b32_e32 v168, 4, v9
	v_bitop3_b32 v9, v6, v10, 6 bitop3:0x36
	v_lshlrev_b32_e32 v169, 4, v9
	v_bitop3_b32 v9, v6, v10, 8 bitop3:0x36
	v_lshlrev_b32_e32 v170, 4, v9
	v_bitop3_b32 v9, v6, v10, 10 bitop3:0x36
	v_lshlrev_b32_e32 v171, 4, v9
	v_bitop3_b32 v9, v6, v10, 12 bitop3:0x36
	v_lshlrev_b32_e32 v172, 4, v9
	v_bitop3_b32 v9, v6, v10, 14 bitop3:0x36
	v_and_or_b32 v6, v0, 3, v174
	v_lshlrev_b32_e32 v5, 1, v5
	v_lshl_add_u64 v[158:159], v[2:3], 1, s[44:45]
	v_add_u32_e32 v2, s22, v4
	v_mov_b32_e32 v50, 0
	v_mul_f32_e32 v8, 0x3fb8aa3b, v8
	v_and_b32_e32 v5, 32, v5
	v_lshl_add_u32 v6, v6, 6, 0
	v_sub_u32_e32 v2, v2, v174
	v_mov_b32_e32 v51, v50
	v_lshlrev_b32_e32 v160, 8, v4
	v_lshlrev_b32_e32 v161, 4, v11
	v_lshlrev_b32_e32 v173, 4, v9
	v_or_b32_e32 v0, s22, v4
	v_add3_u32 v175, v6, v5, v7
	v_cmp_eq_f32_e64 s[40:41], 0, v8
	v_xor_b32_e32 v152, 0x80000000, v8
	v_subrev_u32_e32 v176, s62, v2
	v_mov_b32_e32 v52, v50
	v_mov_b32_e32 v53, v50
	v_mov_b32_e32 v54, v50
	v_mov_b32_e32 v55, v50
	v_mov_b32_e32 v56, v50
	v_mov_b32_e32 v57, v50
	v_mov_b32_e32 v58, v50
	v_mov_b32_e32 v59, v50
	v_mov_b32_e32 v60, v50
	v_mov_b32_e32 v61, v50
	v_mov_b32_e32 v62, v50
	v_mov_b32_e32 v63, v50
	v_mov_b32_e32 v64, v50
	v_mov_b32_e32 v65, v50
	v_mov_b64_e32 v[34:35], v[50:51]
	s_waitcnt lgkmcnt(0)
	v_mov_b64_e32 v[18:19], v[50:51]
	v_mov_b64_e32 v[2:3], v[50:51]
	s_or_b32 s65, s22, 31
	s_add_i32 s66, s22, 0xffffff80
	s_add_i32 s67, s22, 0xffffff9f
	v_mov_b32_e32 v155, v0
	v_mov_b32_e32 v156, v152
	v_mov_b32_e32 v157, v152
	v_mov_b32_e32 v67, 0xf149f2ca
	v_mov_b64_e32 v[36:37], v[52:53]
	v_mov_b64_e32 v[38:39], v[54:55]
	v_mov_b64_e32 v[40:41], v[56:57]
	v_mov_b64_e32 v[42:43], v[58:59]
	v_mov_b64_e32 v[44:45], v[60:61]
	v_mov_b64_e32 v[46:47], v[62:63]
	v_mov_b64_e32 v[48:49], v[64:65]
	v_mov_b64_e32 v[20:21], v[52:53]
	v_mov_b64_e32 v[22:23], v[54:55]
	v_mov_b64_e32 v[24:25], v[56:57]
	v_mov_b64_e32 v[26:27], v[58:59]
	v_mov_b64_e32 v[28:29], v[60:61]
	v_mov_b64_e32 v[30:31], v[62:63]
	v_mov_b64_e32 v[32:33], v[64:65]
	v_mov_b64_e32 v[4:5], v[52:53]
	v_mov_b64_e32 v[6:7], v[54:55]
	v_mov_b64_e32 v[8:9], v[56:57]
	v_mov_b64_e32 v[10:11], v[58:59]
	v_mov_b64_e32 v[12:13], v[60:61]
	v_mov_b64_e32 v[14:15], v[62:63]
	v_mov_b64_e32 v[16:17], v[64:65]
	v_mov_b32_e32 v66, v50
	s_nop 0

; template <int DQK, bool HAS_LSE>
; __device__ __forceinline__ void unit(LAS unsigned char* lds, const Desc& d) {
;     ...
;     { const bf16* qp = d.Q + (long)(32 * w + r) * d.qs + 8 * hi;
; #pragma unroll
;       for (int ks = 0; ks < NKS; ++ks) qr[ks] = *(const bf16x8*)(qp + 16 * ks); }
;     f32x16 o[4];
; #pragma unroll
;     for (int db = 0; db < 4; ++db)
; #pragma unroll
;         for (int i = 0; i < 16; ++i) o[db][i] = 0.f;
;     float m = NEG, l = 0.f;
;     int kso[KINST], vso[2]; bool kpe_[KINST];
; #pragma unroll
;     for (int i = 0; i < KINST; ++i) { const int q = 64 * (KINST * w + i) + lane, row = q / KCH, pos = q % KCH;
;         const int c = (DQK == 192) ? ((pos & ~7) | ((pos & 7) ^ ((row >> 1) & 7))) : (pos ^ (row & 15));
;         kpe_[i] = (DQK == 192) && (c >= 16);
;         kso[i] = kpe_[i] ? row * (int)d.kps + 8 * (c - 16) : row * (int)d.ks + 8 * c; }
; __global__ void __launch_bounds__(NWAVES * 64, 2) mega_fwd(Args args) {
;     ...
;                             const int v = u & 255, i = (u >> 8) & 3, bh = v >> 2, s = v & 3, b = bh / MH, h = bh % MH;
;                             const int qb = (i == 0) ? s : (i == 1) ? 7 - s : (i == 2) ? 8 + s : 15 - s;
;                             fa::Desc dsc;
;                             dsc.Q = QB + (size_t)(b * SEQ + 256 * qb) * NQ + h * QKD; dsc.qs = NQ;
;                             dsc.K = KVB + (size_t)(b * SEQ) * NKV + h * KVROW; dsc.ks = NKV;
;                             dsc.V = dsc.K + NOPE; dsc.vs = NKV; dsc.KPE = KPE + (size_t)(b * SEQ) * (MH * ROPE) + h * ROPE; dsc.kps = MH * ROPE;
;                             dsc.O = MO + (size_t)(b * SEQ + 256 * qb) * D + h * VD; dsc.os = D;
;                             dsc.LSE = nullptr; dsc.lses = 0;
;                             dsc.Q0 = 256 * qb; dsc.t_lo = 0; dsc.t_hi = 4 * qb + 4; dsc.W = 1 << 30; dsc.slope2 = 0.f;
.LBB0_1979:
	s_lshl_b32 s4, s21, 6
	s_and_b32 s15, s4, 0x3000
	s_lshl_b32 s75, s5, 8
	s_add_i32 s22, s75, s15
	s_bfe_u32 s50, s21, 0x40002
	s_mul_i32 s8, s22, 0x1800
	v_readlane_b32 s24, v253, 32
	s_mul_hi_u32 s4, s22, 0x1800
	v_readlane_b32 s25, v253, 33
	s_add_u32 s8, s24, s8
	s_addc_u32 s4, s25, s4
	s_mul_i32 s9, s50, 0x180
	s_add_u32 s8, s8, s9
	v_mov_b32_e32 v5, v204
	s_addc_u32 s9, s4, 0
	v_mov_b64_e32 v[2:3], s[8:9]
	v_readfirstlane_b32 s4, v5
	s_ashr_i32 s4, s4, 6
	v_and_b32_e32 v4, 31, v5
	s_lshl_b32 s47, s4, 5
	v_bfe_u32 v6, v5, 5, 1
	v_or_b32_e32 v0, s47, v4
	v_mad_i64_i32 v[2:3], s[8:9], v0, s11, v[2:3]
	v_lshlrev_b32_e32 v0, 4, v6
	v_lshl_add_u64 v[2:3], v[2:3], 0, v[0:1]
	global_load_dwordx4 v[98:101], v[2:3], off
	global_load_dwordx4 v[102:105], v[2:3], off offset:32
	global_load_dwordx4 v[106:109], v[2:3], off offset:64
	global_load_dwordx4 v[110:113], v[2:3], off offset:96
	global_load_dwordx4 v[114:117], v[2:3], off offset:128
	global_load_dwordx4 v[118:121], v[2:3], off offset:160
	global_load_dwordx4 v[122:125], v[2:3], off offset:192
	global_load_dwordx4 v[126:129], v[2:3], off offset:224
	global_load_dwordx4 v[130:133], v[2:3], off offset:256
	global_load_dwordx4 v[134:137], v[2:3], off offset:288
	global_load_dwordx4 v[138:141], v[2:3], off offset:320
	global_load_dwordx4 v[142:145], v[2:3], off offset:352
	v_and_b32_e32 v0, 63, v5
	s_mul_i32 s8, s4, 0xc0
	v_or_b32_e32 v3, s8, v0
	s_mov_b32 s8, 0x2aaaaaab
	v_mul_hi_i32 v2, v3, s8
	v_lshrrev_b32_e32 v7, 31, v2
	v_ashrrev_i32_e32 v2, 2, v2
	v_add_u32_e32 v2, v2, v7
	v_mul_lo_u32 v7, v2, 24
	v_sub_u32_e32 v3, v3, v7
	v_lshrrev_b32_e32 v7, 1, v2
	v_bitop3_b32 v3, v7, v3, 7 bitop3:0x6c
	v_cmp_lt_i32_e64 s[36:37], 15, v3
	v_cmp_gt_i32_e32 vcc, 16, v3
	v_lshlrev_b32_e32 v3, 3, v3
	s_and_saveexec_b64 s[8:9], vcc
	s_xor_b64 s[8:9], exec, s[8:9]
	v_lshl_add_u32 v168, v2, 12, v3
	s_andn2_saveexec_b64 s[8:9], s[8:9]
	v_lshlrev_b32_e32 v2, 10, v2
	s_movk_i32 s14, 0xff80
	v_add3_u32 v168, v2, v3, s14
	s_or_b64 exec, exec, s[8:9]
	s_mul_i32 s24, s4, 3
	s_add_i32 s14, s24, 1
	v_lshl_or_b32 v3, s14, 6, v0
	s_mov_b32 s8, 0x2aaaaaab
	v_mul_hi_i32 v2, v3, s8
	v_lshrrev_b32_e32 v7, 31, v2
	v_ashrrev_i32_e32 v2, 2, v2
	v_add_u32_e32 v2, v2, v7
	v_mul_lo_u32 v7, v2, 24
	v_sub_u32_e32 v3, v3, v7
	v_lshrrev_b32_e32 v7, 1, v2
	v_bitop3_b32 v3, v7, v3, 7 bitop3:0x6c
	v_cmp_lt_i32_e64 s[38:39], 15, v3
	v_cmp_gt_i32_e32 vcc, 16, v3
	v_lshlrev_b32_e32 v3, 3, v3
	s_and_saveexec_b64 s[8:9], vcc
	s_xor_b64 s[8:9], exec, s[8:9]
	v_lshl_add_u32 v170, v2, 12, v3
	s_andn2_saveexec_b64 s[8:9], s[8:9]
	v_lshlrev_b32_e32 v2, 10, v2
	s_movk_i32 s25, 0xff80
	v_add3_u32 v170, v2, v3, s25
	s_or_b64 exec, exec, s[8:9]
	s_lshl_b32 s8, s15, 13
	v_readlane_b32 s26, v253, 34
	v_readlane_b32 s27, v253, 35
	s_add_u32 s8, s26, s8
	s_addc_u32 s9, s27, 0
	s_lshl_b32 s25, s50, 9
	s_add_u32 s8, s8, s25
	s_addc_u32 s9, s9, 0
	s_lshl_b32 s15, s15, 11
	v_readlane_b32 s26, v253, 36
	v_readlane_b32 s27, v253, 37
	s_add_u32 s15, s26, s15
	s_addc_u32 s25, s27, 0
	s_lshl_b32 s26, s50, 7
	s_add_u32 s42, s15, s26
	s_addc_u32 s43, s25, 0
	s_add_i32 s15, s24, 2
	v_lshl_or_b32 v2, s15, 6, v0
	s_mov_b32 s24, 0x2aaaaaab
	v_mul_hi_i32 v0, v2, s24
	v_lshrrev_b32_e32 v3, 31, v0
	v_ashrrev_i32_e32 v0, 2, v0
	v_add_u32_e32 v0, v0, v3
	v_mul_lo_u32 v3, v0, 24
	v_sub_u32_e32 v2, v2, v3
	v_lshrrev_b32_e32 v3, 1, v0
	v_bitop3_b32 v2, v3, v2, 7 bitop3:0x6c
	v_cmp_lt_i32_e64 s[40:41], 15, v2
	v_cmp_gt_i32_e32 vcc, 16, v2
	v_lshlrev_b32_e32 v7, 3, v2
	s_and_saveexec_b64 s[24:25], vcc
	s_xor_b64 s[44:45], exec, s[24:25]
	v_lshl_add_u32 v172, v0, 12, v7
	s_or_saveexec_b64 s[44:45], s[44:45]
	v_mov_b64_e32 v[2:3], s[8:9]
	s_xor_b64 exec, exec, s[44:45]
	v_lshlrev_b32_e32 v0, 10, v0
	s_movk_i32 s24, 0xff80
	v_add3_u32 v172, v0, v7, s24
	v_mov_b64_e32 v[2:3], s[42:43]
	s_or_b64 exec, exec, s[44:45]
	s_lshr_b32 s24, s21, 2
	s_lshl_b32 s51, s5, 2
	s_lshl_b32 s5, s16, 11
	s_and_b32 s24, s24, 15
	s_and_b32 s5, s5, 0x1800000
	s_lshl_b32 s25, s24, 7
	s_add_i32 s51, s51, 4
	s_add_i32 s52, s47, s75
	s_or_b32 s5, s5, s25
	s_add_u32 s53, s5, 0x2d640000
	s_addc_u32 s56, 0, 0
	s_lshl_b32 s5, s16, 13
	v_lshlrev_b32_e32 v0, 10, v5
	s_and_b32 s5, s5, 0x6000000
	s_lshl_b32 s24, s24, 9
	v_and_b32_e32 v0, 0x7000, v0
	v_lshlrev_b32_e32 v7, 3, v5
	s_or_b32 s44, s5, s24
	v_lshl_or_b32 v0, s4, 15, v0
	v_and_b32_e32 v7, 24, v7
	v_and_b32_e32 v8, 32, v5
	s_add_u32 s57, s44, 0x25700000
	v_or3_b32 v8, v0, v8, v7
	v_mov_b32_e32 v0, s9
	v_mov_b32_e32 v9, s43
	v_mov_b32_e32 v11, s8
	v_mov_b32_e32 v16, s42
	v_ashrrev_i32_e32 v169, 31, v168
	s_mul_i32 s59, s4, 0xc00
	s_addc_u32 s58, 0, 0
	v_cndmask_b32_e64 v13, v0, v9, s[36:37]
	v_cndmask_b32_e64 v12, v11, v16, s[36:37]
	v_lshlrev_b64 v[14:15], 1, v[168:169]
; #define FA_WAIT_NI() do { if constexpr (NI == 5) asm volatile("s_waitcnt vmcnt(5)" ::: "memory"); else asm volatile("s_waitcnt vmcnt(4)" ::: "memory"); } while (0)
; template <int DQK, bool HAS_LSE>
; __device__ __forceinline__ void unit(LAS unsigned char* lds, const Desc& d) {
;     ...
;     int koff[NKO];
; #pragma unroll
;     for (int j = 0; j < NKO; ++j) koff[j] = (DQK == 192) ? (r * KROW + 16 * ((2 * j + hi) ^ ((r >> 1) & 7))) : (r * KROW + 16 * ((2 * j + hi) ^ (r & 15)));
;     const int vfo = LDS_V + (4 * hi + ((lane & 15) >> 2)) * 64 + ((lane >> 4) & 1) * 32 + (lane & 3) * 8;
;     ...
;     constexpr int NI = KINST + 2;
;     ...
;     FA_DMA(d.t_lo, 0, 0);
;     if (d.t_lo + 1 < d.t_hi) { FA_DMA(d.t_lo + 1, 1, 1); FA_WAIT_NI(); } else { asm volatile("s_waitcnt vmcnt(0)" ::: "memory"); }
;     __builtin_amdgcn_s_barrier();
;     int slot = 0;
	s_add_i32 s24, s59, 0
	v_lshl_add_u64 v[12:13], v[12:13], 0, v[14:15]
	s_mov_b32 m0, s24
	v_ashrrev_i32_e32 v171, 31, v170
	s_lshl_b32 s62, s14, 10
	global_load_lds_dwordx4 v[12:13], off
	v_cndmask_b32_e64 v13, v0, v9, s[38:39]
	v_cndmask_b32_e64 v12, v11, v16, s[38:39]
	v_lshlrev_b64 v[16:17], 1, v[170:171]
	s_add_i32 s14, s62, 0
	v_lshl_add_u64 v[12:13], v[12:13], 0, v[16:17]
	s_mov_b32 m0, s14
	v_ashrrev_i32_e32 v173, 31, v172
	s_lshl_b32 s63, s15, 10
	global_load_lds_dwordx4 v[12:13], off
	v_lshlrev_b64 v[12:13], 1, v[172:173]
	s_add_i32 s15, s63, 0
	v_lshl_add_u64 v[2:3], v[2:3], 0, v[12:13]
	s_mov_b32 m0, s15
	s_lshl_b32 s4, s4, 11
	v_ashrrev_i32_e32 v9, 31, v8
	global_load_lds_dwordx4 v[2:3], off
	s_add_i32 s25, s4, 0
	v_lshlrev_b64 v[2:3], 1, v[8:9]
	v_or_b32_e32 v10, 64, v8
	s_add_i32 s64, s25, 0x12000
	v_lshl_add_u64 v[8:9], s[8:9], 0, v[2:3]
	s_mov_b64 s[4:5], 0x100
	s_nop 0
	v_lshl_add_u64 v[18:19], v[8:9], 0, s[4:5]
	s_mov_b32 m0, s64
	s_mov_b64 s[4:5], 0x180
	global_load_lds_dwordx4 v[18:19], off
	s_add_i32 m0, s25, 0x12400
	v_lshl_add_u64 v[8:9], v[8:9], 0, s[4:5]
	s_add_u32 s4, s8, 0x80000
	s_addc_u32 s5, s9, 0
	s_add_u32 s26, s42, 0x20000
	s_addc_u32 s27, s43, 0
	v_mov_b32_e32 v0, s5
	v_mov_b32_e32 v18, s27
	v_mov_b32_e32 v19, s4
	v_mov_b32_e32 v20, s26
	global_load_lds_dwordx4 v[8:9], off
	v_cndmask_b32_e64 v9, v0, v18, s[36:37]
	v_cndmask_b32_e64 v8, v19, v20, s[36:37]
	v_lshl_add_u64 v[8:9], v[8:9], 0, v[14:15]
	s_add_i32 m0, s24, 0x6000
	v_ashrrev_i32_e32 v11, 31, v10
	global_load_lds_dwordx4 v[8:9], off
	v_cndmask_b32_e64 v9, v0, v18, s[38:39]
	v_cndmask_b32_e64 v8, v19, v20, s[38:39]
	v_lshl_add_u64 v[8:9], v[8:9], 0, v[16:17]
	s_add_i32 m0, s14, 0x6000
	v_lshlrev_b32_e32 v182, 2, v6
	global_load_lds_dwordx4 v[8:9], off
	s_add_i32 m0, s15, 0x6000
	v_cndmask_b32_e64 v9, v0, v18, s[40:41]
	v_cndmask_b32_e64 v8, v19, v20, s[40:41]
	s_add_u32 s4, s8, 0x80100
	v_lshl_add_u64 v[8:9], v[8:9], 0, v[12:13]
	s_addc_u32 s5, s9, 0
	global_load_lds_dwordx4 v[8:9], off
	s_add_i32 m0, s25, 0x16000
	v_lshl_add_u64 v[8:9], s[4:5], 0, v[2:3]
	global_load_lds_dwordx4 v[8:9], off
	v_lshl_add_u64 v[8:9], v[10:11], 1, s[4:5]
	s_add_i32 m0, s25, 0x16400
	v_lshrrev_b32_e32 v0, 2, v5
	global_load_lds_dwordx4 v[8:9], off
	v_lshrrev_b32_e32 v8, 1, v5
	v_bfe_u32 v9, v5, 1, 3
	v_bitop3_b32 v8, v6, v8, 7 bitop3:0x78
	v_and_or_b32 v0, v0, 3, v182
	v_lshlrev_b32_e32 v5, 1, v5
	v_lshlrev_b32_e32 v178, 4, v8
	v_bitop3_b32 v8, v6, v9, 2 bitop3:0x36
	v_and_b32_e32 v5, 32, v5
	v_lshlrev_b32_e32 v0, 6, v0
	v_lshlrev_b32_e32 v179, 4, v8
	v_bitop3_b32 v8, v6, v9, 4 bitop3:0x36
	v_add3_u32 v0, 0, v0, v5
	s_mov_b32 s4, 0x12000
	s_mov_b32 s45, s23
	v_lshlrev_b32_e32 v180, 4, v8
	v_bitop3_b32 v8, v6, v9, 6 bitop3:0x36
	v_add3_u32 v183, v0, v7, s4
	v_add_u32_e32 v0, s52, v4
	v_mov_b32_e32 v14, v1
	v_mov_b32_e32 v15, v1
	v_mul_u32_u24_e32 v175, 0x180, v4
	v_lshlrev_b32_e32 v181, 4, v8
	v_or_b32_e32 v174, s52, v4
	s_waitcnt vmcnt(5)
	v_sub_u32_e32 v184, v0, v182
	v_lshl_add_u64 v[176:177], s[44:45], 0, v[2:3]
	v_mov_b32_e32 v0, v1
	v_mov_b32_e32 v2, v1
	v_mov_b32_e32 v3, v1
	v_mov_b32_e32 v4, v1
	v_mov_b32_e32 v5, v1
	v_mov_b32_e32 v6, v1
	v_mov_b32_e32 v7, v1
	v_mov_b32_e32 v8, v1
	v_mov_b32_e32 v9, v1
	v_mov_b32_e32 v10, v1
	v_mov_b32_e32 v11, v1
	v_mov_b32_e32 v12, v1
	v_mov_b32_e32 v13, v1
	v_mov_b64_e32 v[64:65], v[14:15]
	v_mov_b64_e32 v[48:49], v[14:15]
	s_waitcnt lgkmcnt(0)
	v_mov_b64_e32 v[32:33], v[14:15]
	v_mov_b64_e32 v[62:63], v[12:13]
	v_mov_b64_e32 v[60:61], v[10:11]
	v_mov_b64_e32 v[58:59], v[8:9]
	v_mov_b64_e32 v[56:57], v[6:7]
	v_mov_b64_e32 v[54:55], v[4:5]
	v_mov_b64_e32 v[52:53], v[2:3]
	v_mov_b64_e32 v[50:51], v[0:1]
	v_mov_b64_e32 v[46:47], v[12:13]
	v_mov_b64_e32 v[44:45], v[10:11]
	v_mov_b64_e32 v[42:43], v[8:9]
	v_mov_b64_e32 v[40:41], v[6:7]
	v_mov_b64_e32 v[38:39], v[4:5]
	v_mov_b64_e32 v[36:37], v[2:3]
	v_mov_b64_e32 v[34:35], v[0:1]
	v_mov_b64_e32 v[30:31], v[12:13]
	v_mov_b64_e32 v[28:29], v[10:11]
	v_mov_b64_e32 v[26:27], v[8:9]
	v_mov_b64_e32 v[24:25], v[6:7]
	v_mov_b64_e32 v[22:23], v[4:5]
	v_mov_b64_e32 v[20:21], v[2:3]
	v_mov_b64_e32 v[18:19], v[0:1]
	v_mov_b64_e32 v[16:17], v[14:15]
	s_mov_b32 s65, 2
	s_or_b32 s66, s52, 31
	s_add_i32 s67, s52, -2.0
	s_add_i32 s74, s52, 0xc000001f
	v_mov_b32_e32 v167, v174
	s_addk_i32 s75, 0x100
	s_mov_b32 s44, 0
	v_mov_b32_e32 v188, 0xf149f2ca
	v_mov_b32_e32 v187, 0
	v_mov_b64_e32 v[14:15], v[12:13]
	v_mov_b64_e32 v[12:13], v[10:11]
	v_mov_b64_e32 v[10:11], v[8:9]
	v_mov_b64_e32 v[8:9], v[6:7]
	v_mov_b64_e32 v[6:7], v[4:5]
	v_mov_b64_e32 v[4:5], v[2:3]
	v_mov_b64_e32 v[2:3], v[0:1]
	s_mov_b32 s45, 0
	s_barrier
	s_cmp_ge_u32 s65, s51
	s_cselect_b64 s[8:9], -1, 0
	s_and_b64 vcc, exec, s[8:9]
	s_cbranch_vccnz .LBB0_1994
	s_branch .LBB0_1993
